# DA sub-LN epilogues (latent+context): 16 row-per-lane dwordx2 stores widened to 8 dwordx4 via v_permlane32_swap pairs, gain copies removed
# speedup vs baseline: 1.0064x; 1.0050x over previous
.LBB0_728:
	s_mov_b64 s[6:7], 0
	s_cbranch_execz .LBB0_730
	v_mul_f32_e32 v0, v81, v81
	v_fmac_f32_e32 v0, v80, v80
	v_fmac_f32_e32 v0, v82, v82
	v_fmac_f32_e32 v0, v83, v83
	v_fmac_f32_e32 v0, v84, v84
	v_fmac_f32_e32 v0, v85, v85
	v_fmac_f32_e32 v0, v86, v86
	v_fmac_f32_e32 v0, v87, v87
	v_fmac_f32_e32 v0, v88, v88
	v_fmac_f32_e32 v0, v89, v89
	v_fmac_f32_e32 v0, v90, v90
	v_fmac_f32_e32 v0, v91, v91
	v_fmac_f32_e32 v0, v92, v92
	v_fmac_f32_e32 v0, v93, v93
	v_fmac_f32_e32 v0, v94, v94
	v_fmac_f32_e32 v0, v95, v95
	v_fmac_f32_e32 v0, v96, v96
	v_fmac_f32_e32 v0, v97, v97
	v_fmac_f32_e32 v0, v98, v98
	v_fmac_f32_e32 v0, v99, v99
	v_fmac_f32_e32 v0, v100, v100
	v_fmac_f32_e32 v0, v101, v101
	v_fmac_f32_e32 v0, v102, v102
	v_fmac_f32_e32 v0, v103, v103
	v_fmac_f32_e32 v0, v104, v104
	v_fmac_f32_e32 v0, v105, v105
	v_fmac_f32_e32 v0, v106, v106
	v_fmac_f32_e32 v0, v107, v107
	v_fmac_f32_e32 v0, v108, v108
	v_fmac_f32_e32 v0, v109, v109
	v_fmac_f32_e32 v0, v110, v110
	v_fmac_f32_e32 v0, v111, v111
	v_fmac_f32_e32 v0, v112, v112
	v_fmac_f32_e32 v0, v113, v113
	v_fmac_f32_e32 v0, v114, v114
	v_fmac_f32_e32 v0, v115, v115
	v_fmac_f32_e32 v0, v116, v116
	v_fmac_f32_e32 v0, v117, v117
	v_fmac_f32_e32 v0, v118, v118
	v_fmac_f32_e32 v0, v119, v119
	v_fmac_f32_e32 v0, v120, v120
	v_fmac_f32_e32 v0, v121, v121
	v_fmac_f32_e32 v0, v122, v122
	v_fmac_f32_e32 v0, v123, v123
	v_fmac_f32_e32 v0, v124, v124
	v_fmac_f32_e32 v0, v125, v125
	v_fmac_f32_e32 v0, v126, v126
	v_fmac_f32_e32 v0, v127, v127
	v_fmac_f32_e32 v0, v128, v128
	v_fmac_f32_e32 v0, v129, v129
	v_fmac_f32_e32 v0, v130, v130
	v_fmac_f32_e32 v0, v131, v131
	v_fmac_f32_e32 v0, v132, v132
	v_fmac_f32_e32 v0, v133, v133
	v_pk_mul_f32 v[10:11], v[134:135], v[134:135]
	v_pk_mul_f32 v[8:9], v[136:137], v[136:137]
	v_add_f32_e32 v0, v10, v0
	v_add_f32_e32 v0, v11, v0
	v_add_f32_e32 v0, v8, v0
	v_pk_mul_f32 v[6:7], v[138:139], v[138:139]
	v_add_f32_e32 v0, v9, v0
	v_add_f32_e32 v0, v6, v0
	v_pk_mul_f32 v[4:5], v[140:141], v[140:141]
	v_add_f32_e32 v0, v7, v0
	v_add_f32_e32 v0, v4, v0
	v_pk_mul_f32 v[2:3], v[142:143], v[142:143]
	v_add_f32_e32 v0, v5, v0
	v_add_f32_e32 v0, v2, v0
	v_add_f32_e32 v0, v3, v0
	ds_bpermute_b32 v2, v210, v0
	v_and_b32_e32 v185, 31, v240
	v_lshrrev_b32_e32 v184, 5, v194
	v_mov_b32_e32 v12, v184
	v_mov_b32_e32 v13, v185
	s_waitcnt lgkmcnt(0)
	v_add_f32_e32 v0, v0, v2
	v_fmamk_f32 v0, v0, 0x3c000000, v213
	v_cmp_gt_f32_e32 vcc, s79, v0
	v_mul_f32_e32 v2, 0x4b800000, v0
	s_load_dwordx2 s[8:9], s[48:49], 0x88
	v_cndmask_b32_e32 v0, v0, v2, vcc
	v_rsq_f32_e32 v0, v0
	v_readlane_b32 s5, v255, 1
	s_lshl_b32 s5, s5, 2
	s_waitcnt lgkmcnt(0)
	s_add_u32 s8, s8, s5
	v_mul_f32_e32 v2, 0x45800000, v0
	v_cndmask_b32_e32 v0, v0, v2, vcc
	v_add_u32_e32 v2, s4, v13
	v_ashrrev_i32_e32 v3, 31, v2
	v_lshlrev_b32_e32 v10, 2, v12
	s_addc_u32 s9, s9, 0
	v_lshlrev_b64 v[2:3], 11, v[2:3]
	v_readlane_b32 s4, v252, 26
	v_ashrrev_i32_e32 v11, 31, v10
	v_lshl_add_u64 v[2:3], s[0:1], 0, v[2:3]
	s_lshl_b32 s4, s4, 1
	s_mov_b32 s5, s56
	v_lshl_add_u64 v[6:7], v[10:11], 2, s[8:9]
	v_lshl_add_u64 v[8:9], v[2:3], 0, s[4:5]
	global_load_dwordx4 v[16:19], v[6:7], off
	global_load_dwordx4 v[20:23], v[6:7], off offset:32
	global_load_dwordx4 v[24:27], v[6:7], off offset:64
	global_load_dwordx4 v[28:31], v[6:7], off offset:96
	global_load_dwordx4 v[32:35], v[6:7], off offset:128
	global_load_dwordx4 v[36:39], v[6:7], off offset:160
	global_load_dwordx4 v[40:43], v[6:7], off offset:192
	global_load_dwordx4 v[44:47], v[6:7], off offset:224
	global_load_dwordx4 v[48:51], v[6:7], off offset:256
	global_load_dwordx4 v[52:55], v[6:7], off offset:288
	global_load_dwordx4 v[56:59], v[6:7], off offset:320
	global_load_dwordx4 v[60:63], v[6:7], off offset:352
	global_load_dwordx4 v[64:67], v[6:7], off offset:384
	global_load_dwordx4 v[68:71], v[6:7], off offset:416
	global_load_dwordx4 v[72:75], v[6:7], off offset:448
	global_load_dwordx4 v[76:79], v[6:7], off offset:480
	v_mul_f32_e32 v0, v239, v0
	s_waitcnt vmcnt(0)
	v_lshl_add_u64 v[2:3], v[10:11], 2, v[8:9]
	v_pk_mul_f32 v[4:5], v[80:81], v[0:1] op_sel_hi:[1,0]
	v_pk_mul_f32 v[6:7], v[82:83], v[0:1] op_sel_hi:[1,0]
	v_pk_mul_f32 v[8:9], v[84:85], v[0:1] op_sel_hi:[1,0]
	v_pk_mul_f32 v[10:11], v[86:87], v[0:1] op_sel_hi:[1,0]
	v_pk_mul_f32 v[4:5], v[4:5], v[16:17]
	v_pk_mul_f32 v[6:7], v[6:7], v[18:19]
	v_pk_mul_f32 v[8:9], v[8:9], v[20:21]
	v_pk_mul_f32 v[10:11], v[10:11], v[22:23]
	v_cvt_pk_bf16_f32 v12, v4, v5
	v_cvt_pk_bf16_f32 v13, v6, v7
	v_cvt_pk_bf16_f32 v14, v8, v9
	v_cvt_pk_bf16_f32 v15, v10, v11
	s_nop 1
	v_permlane32_swap_b32_e32 v12, v14
	v_permlane32_swap_b32_e32 v13, v15
	global_store_dwordx4 v[2:3], v[12:15], off
	v_pk_mul_f32 v[4:5], v[88:89], v[0:1] op_sel_hi:[1,0]
	v_pk_mul_f32 v[6:7], v[90:91], v[0:1] op_sel_hi:[1,0]
	v_pk_mul_f32 v[8:9], v[92:93], v[0:1] op_sel_hi:[1,0]
	v_pk_mul_f32 v[10:11], v[94:95], v[0:1] op_sel_hi:[1,0]
	v_pk_mul_f32 v[4:5], v[4:5], v[24:25]
	v_pk_mul_f32 v[6:7], v[6:7], v[26:27]
	v_pk_mul_f32 v[8:9], v[8:9], v[28:29]
	v_pk_mul_f32 v[10:11], v[10:11], v[30:31]
	v_cvt_pk_bf16_f32 v12, v4, v5
	v_cvt_pk_bf16_f32 v13, v6, v7
	v_cvt_pk_bf16_f32 v14, v8, v9
	v_cvt_pk_bf16_f32 v15, v10, v11
	s_nop 1
	v_permlane32_swap_b32_e32 v12, v14
	v_permlane32_swap_b32_e32 v13, v15
	global_store_dwordx4 v[2:3], v[12:15], off offset:32
	v_pk_mul_f32 v[4:5], v[96:97], v[0:1] op_sel_hi:[1,0]
	v_pk_mul_f32 v[6:7], v[98:99], v[0:1] op_sel_hi:[1,0]
	v_pk_mul_f32 v[8:9], v[100:101], v[0:1] op_sel_hi:[1,0]
	v_pk_mul_f32 v[10:11], v[102:103], v[0:1] op_sel_hi:[1,0]
	v_pk_mul_f32 v[4:5], v[4:5], v[32:33]
	v_pk_mul_f32 v[6:7], v[6:7], v[34:35]
	v_pk_mul_f32 v[8:9], v[8:9], v[36:37]
	v_pk_mul_f32 v[10:11], v[10:11], v[38:39]
	v_cvt_pk_bf16_f32 v12, v4, v5
	v_cvt_pk_bf16_f32 v13, v6, v7
	v_cvt_pk_bf16_f32 v14, v8, v9
	v_cvt_pk_bf16_f32 v15, v10, v11
	s_nop 1
	v_permlane32_swap_b32_e32 v12, v14
	v_permlane32_swap_b32_e32 v13, v15
	global_store_dwordx4 v[2:3], v[12:15], off offset:64
	v_pk_mul_f32 v[4:5], v[104:105], v[0:1] op_sel_hi:[1,0]
	v_pk_mul_f32 v[6:7], v[106:107], v[0:1] op_sel_hi:[1,0]
	v_pk_mul_f32 v[8:9], v[108:109], v[0:1] op_sel_hi:[1,0]
	v_pk_mul_f32 v[10:11], v[110:111], v[0:1] op_sel_hi:[1,0]
	v_pk_mul_f32 v[4:5], v[4:5], v[40:41]
	v_pk_mul_f32 v[6:7], v[6:7], v[42:43]
	v_pk_mul_f32 v[8:9], v[8:9], v[44:45]
	v_pk_mul_f32 v[10:11], v[10:11], v[46:47]
	v_cvt_pk_bf16_f32 v12, v4, v5
	v_cvt_pk_bf16_f32 v13, v6, v7
	v_cvt_pk_bf16_f32 v14, v8, v9
	v_cvt_pk_bf16_f32 v15, v10, v11
	s_nop 1
	v_permlane32_swap_b32_e32 v12, v14
	v_permlane32_swap_b32_e32 v13, v15
	global_store_dwordx4 v[2:3], v[12:15], off offset:96
	v_pk_mul_f32 v[4:5], v[112:113], v[0:1] op_sel_hi:[1,0]
	v_pk_mul_f32 v[6:7], v[114:115], v[0:1] op_sel_hi:[1,0]
	v_pk_mul_f32 v[8:9], v[116:117], v[0:1] op_sel_hi:[1,0]
	v_pk_mul_f32 v[10:11], v[118:119], v[0:1] op_sel_hi:[1,0]
	v_pk_mul_f32 v[4:5], v[4:5], v[48:49]
	v_pk_mul_f32 v[6:7], v[6:7], v[50:51]
	v_pk_mul_f32 v[8:9], v[8:9], v[52:53]
	v_pk_mul_f32 v[10:11], v[10:11], v[54:55]
	v_cvt_pk_bf16_f32 v12, v4, v5
	v_cvt_pk_bf16_f32 v13, v6, v7
	v_cvt_pk_bf16_f32 v14, v8, v9
	v_cvt_pk_bf16_f32 v15, v10, v11
	s_nop 1
	v_permlane32_swap_b32_e32 v12, v14
	v_permlane32_swap_b32_e32 v13, v15
	global_store_dwordx4 v[2:3], v[12:15], off offset:128
	v_pk_mul_f32 v[4:5], v[120:121], v[0:1] op_sel_hi:[1,0]
	v_pk_mul_f32 v[6:7], v[122:123], v[0:1] op_sel_hi:[1,0]
	v_pk_mul_f32 v[8:9], v[124:125], v[0:1] op_sel_hi:[1,0]
	v_pk_mul_f32 v[10:11], v[126:127], v[0:1] op_sel_hi:[1,0]
	v_pk_mul_f32 v[4:5], v[4:5], v[56:57]
	v_pk_mul_f32 v[6:7], v[6:7], v[58:59]
	v_pk_mul_f32 v[8:9], v[8:9], v[60:61]
	v_pk_mul_f32 v[10:11], v[10:11], v[62:63]
	v_cvt_pk_bf16_f32 v12, v4, v5
	v_cvt_pk_bf16_f32 v13, v6, v7
	v_cvt_pk_bf16_f32 v14, v8, v9
	v_cvt_pk_bf16_f32 v15, v10, v11
	s_nop 1
	v_permlane32_swap_b32_e32 v12, v14
	v_permlane32_swap_b32_e32 v13, v15
	global_store_dwordx4 v[2:3], v[12:15], off offset:160
	v_pk_mul_f32 v[4:5], v[128:129], v[0:1] op_sel_hi:[1,0]
	v_pk_mul_f32 v[6:7], v[130:131], v[0:1] op_sel_hi:[1,0]
	v_pk_mul_f32 v[8:9], v[132:133], v[0:1] op_sel_hi:[1,0]
	v_pk_mul_f32 v[10:11], v[134:135], v[0:1] op_sel_hi:[1,0]
	v_pk_mul_f32 v[4:5], v[4:5], v[64:65]
	v_pk_mul_f32 v[6:7], v[6:7], v[66:67]
	v_pk_mul_f32 v[8:9], v[8:9], v[68:69]
	v_pk_mul_f32 v[10:11], v[10:11], v[70:71]
	v_cvt_pk_bf16_f32 v12, v4, v5
	v_cvt_pk_bf16_f32 v13, v6, v7
	v_cvt_pk_bf16_f32 v14, v8, v9
	v_cvt_pk_bf16_f32 v15, v10, v11
	s_nop 1
	v_permlane32_swap_b32_e32 v12, v14
	v_permlane32_swap_b32_e32 v13, v15
	global_store_dwordx4 v[2:3], v[12:15], off offset:192
	v_pk_mul_f32 v[4:5], v[136:137], v[0:1] op_sel_hi:[1,0]
	v_pk_mul_f32 v[6:7], v[138:139], v[0:1] op_sel_hi:[1,0]
	v_pk_mul_f32 v[8:9], v[140:141], v[0:1] op_sel_hi:[1,0]
	v_pk_mul_f32 v[10:11], v[142:143], v[0:1] op_sel_hi:[1,0]
	v_pk_mul_f32 v[4:5], v[4:5], v[72:73]
	v_pk_mul_f32 v[6:7], v[6:7], v[74:75]
	v_pk_mul_f32 v[8:9], v[8:9], v[76:77]
	v_pk_mul_f32 v[10:11], v[10:11], v[78:79]
	v_cvt_pk_bf16_f32 v12, v4, v5
	v_cvt_pk_bf16_f32 v13, v6, v7
	v_cvt_pk_bf16_f32 v14, v8, v9
	v_cvt_pk_bf16_f32 v15, v10, v11
	s_nop 1
	v_permlane32_swap_b32_e32 v12, v14
	v_permlane32_swap_b32_e32 v13, v15
	global_store_dwordx4 v[2:3], v[12:15], off offset:224

.LBB0_744:
	v_mul_f32_e32 v0, v129, v129
	v_fmac_f32_e32 v0, v128, v128
	v_fmac_f32_e32 v0, v130, v130
	v_fmac_f32_e32 v0, v131, v131
	v_fmac_f32_e32 v0, v132, v132
	v_fmac_f32_e32 v0, v133, v133
	v_fmac_f32_e32 v0, v134, v134
	v_fmac_f32_e32 v0, v135, v135
	v_fmac_f32_e32 v0, v136, v136
	v_fmac_f32_e32 v0, v137, v137
	v_fmac_f32_e32 v0, v138, v138
	v_fmac_f32_e32 v0, v139, v139
	v_fmac_f32_e32 v0, v140, v140
	v_fmac_f32_e32 v0, v141, v141
	v_fmac_f32_e32 v0, v142, v142
	v_fmac_f32_e32 v0, v143, v143
	v_fmac_f32_e32 v0, v112, v112
	v_fmac_f32_e32 v0, v113, v113
	v_fmac_f32_e32 v0, v114, v114
	v_fmac_f32_e32 v0, v115, v115
	v_fmac_f32_e32 v0, v116, v116
	v_fmac_f32_e32 v0, v117, v117
	v_fmac_f32_e32 v0, v118, v118
	v_fmac_f32_e32 v0, v119, v119
	v_fmac_f32_e32 v0, v120, v120
	v_fmac_f32_e32 v0, v121, v121
	v_fmac_f32_e32 v0, v122, v122
	v_fmac_f32_e32 v0, v123, v123
	v_fmac_f32_e32 v0, v124, v124
	v_fmac_f32_e32 v0, v125, v125
	v_fmac_f32_e32 v0, v126, v126
	v_fmac_f32_e32 v0, v127, v127
	v_fmac_f32_e32 v0, v96, v96
	v_fmac_f32_e32 v0, v97, v97
	v_fmac_f32_e32 v0, v98, v98
	v_fmac_f32_e32 v0, v99, v99
	v_fmac_f32_e32 v0, v100, v100
	v_fmac_f32_e32 v0, v101, v101
	v_fmac_f32_e32 v0, v102, v102
	v_fmac_f32_e32 v0, v103, v103
	v_fmac_f32_e32 v0, v104, v104
	v_fmac_f32_e32 v0, v105, v105
	v_fmac_f32_e32 v0, v106, v106
	v_fmac_f32_e32 v0, v107, v107
	v_fmac_f32_e32 v0, v108, v108
	v_fmac_f32_e32 v0, v109, v109
	v_fmac_f32_e32 v0, v110, v110
	v_fmac_f32_e32 v0, v111, v111
	v_fmac_f32_e32 v0, v80, v80
	v_fmac_f32_e32 v0, v81, v81
	v_fmac_f32_e32 v0, v82, v82
	v_fmac_f32_e32 v0, v83, v83
	v_fmac_f32_e32 v0, v84, v84
	v_fmac_f32_e32 v0, v85, v85
	v_pk_mul_f32 v[10:11], v[86:87], v[86:87]
	v_pk_mul_f32 v[8:9], v[88:89], v[88:89]
	v_add_f32_e32 v0, v10, v0
	v_add_f32_e32 v0, v11, v0
	v_add_f32_e32 v0, v8, v0
	v_pk_mul_f32 v[6:7], v[90:91], v[90:91]
	v_add_f32_e32 v0, v9, v0
	v_add_f32_e32 v0, v6, v0
	v_pk_mul_f32 v[4:5], v[92:93], v[92:93]
	v_add_f32_e32 v0, v7, v0
	v_add_f32_e32 v0, v4, v0
	v_pk_mul_f32 v[2:3], v[94:95], v[94:95]
	v_add_f32_e32 v0, v5, v0
	v_add_f32_e32 v0, v2, v0
	v_add_f32_e32 v0, v3, v0
	ds_bpermute_b32 v2, v210, v0
	s_load_dwordx2 s[8:9], s[48:49], 0x88
	v_readlane_b32 s5, v255, 1
	s_lshl_b32 s5, s5, 2
	s_waitcnt lgkmcnt(0)
	v_add_f32_e32 v0, v0, v2
	v_fmamk_f32 v0, v0, 0x3c000000, v213
	v_cmp_gt_f32_e32 vcc, s79, v0
	v_mul_f32_e32 v2, 0x4b800000, v0
	s_add_u32 s8, s8, s5
	v_cndmask_b32_e32 v0, v0, v2, vcc
	v_rsq_f32_e32 v0, v0
	v_lshlrev_b32_e32 v10, 2, v184
	s_addc_u32 s9, s9, 0
	v_ashrrev_i32_e32 v11, 31, v10
	v_mul_f32_e32 v2, 0x45800000, v0
	v_cndmask_b32_e32 v0, v0, v2, vcc
	v_add_u32_e32 v2, s4, v185
	v_ashrrev_i32_e32 v3, 31, v2
	v_lshlrev_b64 v[2:3], 11, v[2:3]
	v_lshl_add_u64 v[2:3], s[0:1], 0, v[2:3]
	s_mov_b32 s7, s56
	v_lshl_add_u64 v[6:7], v[10:11], 2, s[8:9]
	v_lshl_add_u64 v[8:9], v[2:3], 0, s[6:7]
	global_load_dwordx4 v[16:19], v[6:7], off
	global_load_dwordx4 v[20:23], v[6:7], off offset:32
	global_load_dwordx4 v[24:27], v[6:7], off offset:64
	global_load_dwordx4 v[28:31], v[6:7], off offset:96
	global_load_dwordx4 v[32:35], v[6:7], off offset:128
	global_load_dwordx4 v[36:39], v[6:7], off offset:160
	global_load_dwordx4 v[40:43], v[6:7], off offset:192
	global_load_dwordx4 v[44:47], v[6:7], off offset:224
	global_load_dwordx4 v[48:51], v[6:7], off offset:256
	global_load_dwordx4 v[52:55], v[6:7], off offset:288
	global_load_dwordx4 v[56:59], v[6:7], off offset:320
	global_load_dwordx4 v[60:63], v[6:7], off offset:352
	global_load_dwordx4 v[64:67], v[6:7], off offset:384
	global_load_dwordx4 v[68:71], v[6:7], off offset:416
	global_load_dwordx4 v[72:75], v[6:7], off offset:448
	global_load_dwordx4 v[76:79], v[6:7], off offset:480
	v_mul_f32_e32 v0, v239, v0
	s_waitcnt vmcnt(0)
	v_lshl_add_u64 v[2:3], v[10:11], 2, v[8:9]
	v_pk_mul_f32 v[4:5], v[128:129], v[0:1] op_sel_hi:[1,0]
	v_pk_mul_f32 v[6:7], v[130:131], v[0:1] op_sel_hi:[1,0]
	v_pk_mul_f32 v[8:9], v[132:133], v[0:1] op_sel_hi:[1,0]
	v_pk_mul_f32 v[10:11], v[134:135], v[0:1] op_sel_hi:[1,0]
	v_pk_mul_f32 v[4:5], v[4:5], v[16:17]
	v_pk_mul_f32 v[6:7], v[6:7], v[18:19]
	v_pk_mul_f32 v[8:9], v[8:9], v[20:21]
	v_pk_mul_f32 v[10:11], v[10:11], v[22:23]
	v_cvt_pk_bf16_f32 v12, v4, v5
	v_cvt_pk_bf16_f32 v13, v6, v7
	v_cvt_pk_bf16_f32 v14, v8, v9
	v_cvt_pk_bf16_f32 v15, v10, v11
	s_nop 1
	v_permlane32_swap_b32_e32 v12, v14
	v_permlane32_swap_b32_e32 v13, v15
	global_store_dwordx4 v[2:3], v[12:15], off
	v_pk_mul_f32 v[4:5], v[136:137], v[0:1] op_sel_hi:[1,0]
	v_pk_mul_f32 v[6:7], v[138:139], v[0:1] op_sel_hi:[1,0]
	v_pk_mul_f32 v[8:9], v[140:141], v[0:1] op_sel_hi:[1,0]
	v_pk_mul_f32 v[10:11], v[142:143], v[0:1] op_sel_hi:[1,0]
	v_pk_mul_f32 v[4:5], v[4:5], v[24:25]
	v_pk_mul_f32 v[6:7], v[6:7], v[26:27]
	v_pk_mul_f32 v[8:9], v[8:9], v[28:29]
	v_pk_mul_f32 v[10:11], v[10:11], v[30:31]
	v_cvt_pk_bf16_f32 v12, v4, v5
	v_cvt_pk_bf16_f32 v13, v6, v7
	v_cvt_pk_bf16_f32 v14, v8, v9
	v_cvt_pk_bf16_f32 v15, v10, v11
	s_nop 1
	v_permlane32_swap_b32_e32 v12, v14
	v_permlane32_swap_b32_e32 v13, v15
	global_store_dwordx4 v[2:3], v[12:15], off offset:32
	v_pk_mul_f32 v[4:5], v[112:113], v[0:1] op_sel_hi:[1,0]
	v_pk_mul_f32 v[6:7], v[114:115], v[0:1] op_sel_hi:[1,0]
	v_pk_mul_f32 v[8:9], v[116:117], v[0:1] op_sel_hi:[1,0]
	v_pk_mul_f32 v[10:11], v[118:119], v[0:1] op_sel_hi:[1,0]
	v_pk_mul_f32 v[4:5], v[4:5], v[32:33]
	v_pk_mul_f32 v[6:7], v[6:7], v[34:35]
	v_pk_mul_f32 v[8:9], v[8:9], v[36:37]
	v_pk_mul_f32 v[10:11], v[10:11], v[38:39]
	v_cvt_pk_bf16_f32 v12, v4, v5
	v_cvt_pk_bf16_f32 v13, v6, v7
	v_cvt_pk_bf16_f32 v14, v8, v9
	v_cvt_pk_bf16_f32 v15, v10, v11
	s_nop 1
	v_permlane32_swap_b32_e32 v12, v14
	v_permlane32_swap_b32_e32 v13, v15
	global_store_dwordx4 v[2:3], v[12:15], off offset:64
	v_pk_mul_f32 v[4:5], v[120:121], v[0:1] op_sel_hi:[1,0]
	v_pk_mul_f32 v[6:7], v[122:123], v[0:1] op_sel_hi:[1,0]
	v_pk_mul_f32 v[8:9], v[124:125], v[0:1] op_sel_hi:[1,0]
	v_pk_mul_f32 v[10:11], v[126:127], v[0:1] op_sel_hi:[1,0]
	v_pk_mul_f32 v[4:5], v[4:5], v[40:41]
	v_pk_mul_f32 v[6:7], v[6:7], v[42:43]
	v_pk_mul_f32 v[8:9], v[8:9], v[44:45]
	v_pk_mul_f32 v[10:11], v[10:11], v[46:47]
	v_cvt_pk_bf16_f32 v12, v4, v5
	v_cvt_pk_bf16_f32 v13, v6, v7
	v_cvt_pk_bf16_f32 v14, v8, v9
	v_cvt_pk_bf16_f32 v15, v10, v11
	s_nop 1
	v_permlane32_swap_b32_e32 v12, v14
	v_permlane32_swap_b32_e32 v13, v15
	global_store_dwordx4 v[2:3], v[12:15], off offset:96
	v_pk_mul_f32 v[4:5], v[96:97], v[0:1] op_sel_hi:[1,0]
	v_pk_mul_f32 v[6:7], v[98:99], v[0:1] op_sel_hi:[1,0]
	v_pk_mul_f32 v[8:9], v[100:101], v[0:1] op_sel_hi:[1,0]
	v_pk_mul_f32 v[10:11], v[102:103], v[0:1] op_sel_hi:[1,0]
	v_pk_mul_f32 v[4:5], v[4:5], v[48:49]
	v_pk_mul_f32 v[6:7], v[6:7], v[50:51]
	v_pk_mul_f32 v[8:9], v[8:9], v[52:53]
	v_pk_mul_f32 v[10:11], v[10:11], v[54:55]
	v_cvt_pk_bf16_f32 v12, v4, v5
	v_cvt_pk_bf16_f32 v13, v6, v7
	v_cvt_pk_bf16_f32 v14, v8, v9
	v_cvt_pk_bf16_f32 v15, v10, v11
	s_nop 1
	v_permlane32_swap_b32_e32 v12, v14
	v_permlane32_swap_b32_e32 v13, v15
	global_store_dwordx4 v[2:3], v[12:15], off offset:128
	v_pk_mul_f32 v[4:5], v[104:105], v[0:1] op_sel_hi:[1,0]
	v_pk_mul_f32 v[6:7], v[106:107], v[0:1] op_sel_hi:[1,0]
	v_pk_mul_f32 v[8:9], v[108:109], v[0:1] op_sel_hi:[1,0]
	v_pk_mul_f32 v[10:11], v[110:111], v[0:1] op_sel_hi:[1,0]
	v_pk_mul_f32 v[4:5], v[4:5], v[56:57]
	v_pk_mul_f32 v[6:7], v[6:7], v[58:59]
	v_pk_mul_f32 v[8:9], v[8:9], v[60:61]
	v_pk_mul_f32 v[10:11], v[10:11], v[62:63]
	v_cvt_pk_bf16_f32 v12, v4, v5
	v_cvt_pk_bf16_f32 v13, v6, v7
	v_cvt_pk_bf16_f32 v14, v8, v9
	v_cvt_pk_bf16_f32 v15, v10, v11
	s_nop 1
	v_permlane32_swap_b32_e32 v12, v14
	v_permlane32_swap_b32_e32 v13, v15
	global_store_dwordx4 v[2:3], v[12:15], off offset:160
	v_pk_mul_f32 v[4:5], v[80:81], v[0:1] op_sel_hi:[1,0]
	v_pk_mul_f32 v[6:7], v[82:83], v[0:1] op_sel_hi:[1,0]
	v_pk_mul_f32 v[8:9], v[84:85], v[0:1] op_sel_hi:[1,0]
	v_pk_mul_f32 v[10:11], v[86:87], v[0:1] op_sel_hi:[1,0]
	v_pk_mul_f32 v[4:5], v[4:5], v[64:65]
	v_pk_mul_f32 v[6:7], v[6:7], v[66:67]
	v_pk_mul_f32 v[8:9], v[8:9], v[68:69]
	v_pk_mul_f32 v[10:11], v[10:11], v[70:71]
	v_cvt_pk_bf16_f32 v12, v4, v5
	v_cvt_pk_bf16_f32 v13, v6, v7
	v_cvt_pk_bf16_f32 v14, v8, v9
	v_cvt_pk_bf16_f32 v15, v10, v11
	s_nop 1
	v_permlane32_swap_b32_e32 v12, v14
	v_permlane32_swap_b32_e32 v13, v15
	global_store_dwordx4 v[2:3], v[12:15], off offset:192
	v_pk_mul_f32 v[4:5], v[88:89], v[0:1] op_sel_hi:[1,0]
	v_pk_mul_f32 v[6:7], v[90:91], v[0:1] op_sel_hi:[1,0]
	v_pk_mul_f32 v[8:9], v[92:93], v[0:1] op_sel_hi:[1,0]
	v_pk_mul_f32 v[10:11], v[94:95], v[0:1] op_sel_hi:[1,0]
	v_pk_mul_f32 v[4:5], v[4:5], v[72:73]
	v_pk_mul_f32 v[6:7], v[6:7], v[74:75]
	v_pk_mul_f32 v[8:9], v[8:9], v[76:77]
	v_pk_mul_f32 v[10:11], v[10:11], v[78:79]
	v_cvt_pk_bf16_f32 v12, v4, v5
	v_cvt_pk_bf16_f32 v13, v6, v7
	v_cvt_pk_bf16_f32 v14, v8, v9
	v_cvt_pk_bf16_f32 v15, v10, v11
	s_nop 1
	v_permlane32_swap_b32_e32 v12, v14
	v_permlane32_swap_b32_e32 v13, v15
	global_store_dwordx4 v[2:3], v[12:15], off offset:224
